# latent attention: all K/V-g0 fragment LDS reads issued upfront in QK; V tile LDS layout readable by ds_read_b128; MIX queue order attention-before-DFT; N2 norm loop prefetches params+row one token ahe
# speedup vs baseline: 1.0086x; 1.0037x over previous
.LBB0_94:
	s_andn2_b64 vcc, exec, s[0:1]
	s_cbranch_vccnz .LBB0_101
	v_mov_b32_e32 v6, v228
	v_readlane_b32 s0, v253, 0
	v_mov_b32_e32 v0, v228
	s_mov_b32 s1, 0x9000
	v_ashrrev_i32_e32 v0, 6, v0
	v_lshl_add_u32 v46, s0, 3, v0
	s_mov_b32 s0, s90
	v_cmp_gt_i32_e32 vcc, s1, v46
	s_and_saveexec_b64 s[4:5], vcc
	s_cbranch_execz .LBB0_100
	v_ashrrev_i32_e32 v47, 31, v46
	v_readlane_b32 s24, v254, 21
	v_lshlrev_b32_e32 v0, 2, v6
	v_lshlrev_b64 v[2:3], 12, v[46:47]
	v_readlane_b32 s25, v254, 22
	v_and_b32_e32 v8, 0xfc, v0
	v_lshlrev_b32_e32 v0, 2, v8
	v_lshl_add_u64 v[2:3], s[24:25], 0, v[2:3]
	v_lshl_add_u64 v[2:3], v[2:3], 0, v[0:1]
	global_load_dwordx4 v[30:33], v[2:3], off
	global_load_dwordx4 v[26:29], v[2:3], off offset:1024
	global_load_dwordx4 v[10:13], v[2:3], off offset:2048
	s_waitcnt lgkmcnt(0)
	global_load_dwordx4 v[2:5], v[2:3], off offset:3072
	v_and_b32_e32 v7, 64, v231
	v_add_u32_e32 v7, 64, v7
	v_xor_b32_e32 v9, 1, v231
	v_cmp_lt_i32_e32 vcc, v9, v7
	s_lshl_b32 s6, s0, 3
	v_readlane_b32 s0, v254, 23
	v_cndmask_b32_e32 v9, v231, v9, vcc
	s_waitcnt vmcnt(0)
	v_lshlrev_b32_e32 v52, 2, v9
	v_xor_b32_e32 v9, 2, v231
	v_cmp_lt_i32_e32 vcc, v9, v7
	v_readlane_b32 s1, v254, 24
	s_mov_b32 s8, s0
	v_cndmask_b32_e32 v9, v231, v9, vcc
	v_lshlrev_b32_e32 v53, 2, v9
	v_xor_b32_e32 v9, 4, v231
	v_cmp_lt_i32_e32 vcc, v9, v7
	s_mul_i32 s1, s8, 0x36000
	s_mul_hi_i32 s0, s0, 0x36000
	v_cndmask_b32_e32 v9, v231, v9, vcc
	v_lshlrev_b32_e32 v54, 2, v9
	v_xor_b32_e32 v9, 8, v231
	s_add_u32 s3, s78, s1
	v_cmp_lt_i32_e32 vcc, v9, v7
	s_addc_u32 s7, s79, s0
	s_lshl_b32 s0, s8, 10
	v_cndmask_b32_e32 v9, v231, v9, vcc
	s_ashr_i32 s1, s0, 31
	v_readlane_b32 s8, v253, 51
	v_lshlrev_b32_e32 v55, 2, v9
	v_xor_b32_e32 v9, 16, v231
	s_lshl_b64 s[0:1], s[0:1], 2
	v_readlane_b32 s12, v253, 55
	v_cmp_lt_i32_e32 vcc, v9, v7
	v_readlane_b32 s13, v253, 56
	s_add_u32 s0, s12, s0
	v_cndmask_b32_e32 v9, v231, v9, vcc
	s_addc_u32 s1, s13, s1
	v_lshlrev_b32_e32 v56, 2, v9
	v_xor_b32_e32 v9, 32, v231
	v_cmp_lt_i32_e32 vcc, v9, v7
	v_lshl_add_u64 v[34:35], s[0:1], 0, v[0:1]
	v_lshlrev_b64 v[20:21], 11, v[46:47]
	v_and_b32_e32 v0, 63, v6
	v_cndmask_b32_e32 v7, v231, v9, vcc
	v_lshl_or_b32 v20, v0, 3, v20
	v_lshlrev_b32_e32 v57, 2, v7
	v_lshl_add_u64 v[6:7], s[78:79], 0, v[20:21]
	s_mov_b64 s[0:1], 0x6400000
	v_lshl_add_u64 v[36:37], v[6:7], 0, s[0:1]
	v_add_u32_e32 v6, s6, v46
	v_ashrrev_i32_e32 v7, 31, v6
	v_readlane_b32 s9, v253, 52
	s_add_u32 s8, s3, 0x1d483000
	v_lshlrev_b64 v[6:7], 12, v[6:7]
	v_readlane_b32 s10, v253, 53
	v_readlane_b32 s11, v253, 54
	v_readlane_b32 s14, v253, 57
	v_readlane_b32 s15, v253, 58
	s_addc_u32 s9, s7, 0
	v_or_b32_e32 v14, 0x100, v8
	v_or_b32_e32 v16, 0x200, v8
	v_or_b32_e32 v18, 0x300, v8
	s_ashr_i32 s7, s6, 31
	v_lshl_or_b32 v6, v0, 4, v6
	s_lshl_b64 s[10:11], s[6:7], 11
	v_lshl_add_u64 v[38:39], s[24:25], 0, v[6:7]
	s_lshl_b64 s[12:13], s[6:7], 12
	s_mov_b64 s[14:15], 0
	v_lshlrev_b32_e32 v0, 2, v8
	v_lshlrev_b32_e32 v40, 2, v14
	v_lshlrev_b32_e32 v42, 2, v16
	v_lshlrev_b32_e32 v44, 2, v18
	v_readlane_b32 s16, v253, 59
	v_readlane_b32 s17, v253, 60
	v_readlane_b32 s18, v253, 61
	v_readlane_b32 s19, v253, 62
	v_readlane_b32 s20, v253, 63
	v_readlane_b32 s21, v254, 0
	v_readlane_b32 s22, v254, 1
	v_readlane_b32 s23, v254, 2
	global_load_dwordx4 v[72:75], v[34:35], off
	global_load_dwordx4 v[76:79], v[34:35], off offset:1024
	global_load_dwordx4 v[80:83], v[34:35], off offset:2048
	global_load_dwordx4 v[84:87], v[34:35], off offset:3072
	v_add_u32_e32 v156, 0xfffff000, v46
	v_lshrrev_b32_e32 v156, 12, v156
	v_add_u32_e32 v156, 1, v156
	s_movk_i32 s0, 0xfff
	v_cmp_lt_i32_e32 vcc, s0, v46
	v_mov_b64_e32 v[152:153], s[8:9]
	s_nop 1
	v_cndmask_b32_e32 v156, 0, v156, vcc
	s_nop 0
	v_mad_u64_u32 v[152:153], s[0:1], v156, s89, v[152:153]
	s_mov_b64 s[0:1], 0x1000
	s_nop 0
	v_lshl_add_u64 v[152:153], v[152:153], 0, v[0:1]
	v_lshl_add_u64 v[154:155], v[152:153], 0, s[0:1]
	global_load_dwordx4 v[120:123], v[152:153], off
	global_load_dwordx4 v[124:127], v[152:153], off offset:1024
	global_load_dwordx4 v[128:131], v[152:153], off offset:2048
	global_load_dwordx4 v[132:135], v[152:153], off offset:3072
	global_load_dwordx4 v[136:139], v[154:155], off
	global_load_dwordx4 v[140:143], v[154:155], off offset:1024
	global_load_dwordx4 v[144:147], v[154:155], off offset:2048
	global_load_dwordx4 v[148:151], v[154:155], off offset:3072
	v_mov_b32_e32 v14, v30
	v_mov_b32_e32 v15, v31
	v_mov_b32_e32 v16, v32
	v_mov_b32_e32 v17, v33
	v_mov_b32_e32 v18, v26
	v_mov_b32_e32 v19, v27
	v_mov_b32_e32 v20, v28
	v_mov_b32_e32 v21, v29
	v_mov_b32_e32 v22, v10
	v_mov_b32_e32 v23, v11
	v_mov_b32_e32 v24, v12
	v_mov_b32_e32 v25, v13
	v_mov_b32_e32 v6, v2
	v_mov_b32_e32 v7, v3
	v_mov_b32_e32 v8, v4
	v_mov_b32_e32 v9, v5
	s_branch .LBB0_98
.LBB0_98:
	v_add_u32_e32 v47, s6, v46
	s_mov_b32 s0, 0x9000
	s_mov_b32 s3, 0x8fff
	v_cmp_gt_i32_e64 s[0:1], s0, v47
	v_cmp_lt_i32_e32 vcc, s3, v47
	s_waitcnt vmcnt(0)
	s_nop 0
	s_and_b64 s[16:17], exec, vcc
	s_or_b64 s[14:15], s[16:17], s[14:15]
	v_mov_b32_e32 v30, v14
	v_mov_b32_e32 v31, v15
	v_mov_b32_e32 v32, v16
	v_mov_b32_e32 v33, v17
	v_mov_b32_e32 v26, v18
	v_mov_b32_e32 v27, v19
	v_mov_b32_e32 v28, v20
	v_mov_b32_e32 v29, v21
	v_mov_b32_e32 v10, v22
	v_mov_b32_e32 v11, v23
	v_mov_b32_e32 v12, v24
	v_mov_b32_e32 v13, v25
	v_mov_b32_e32 v2, v6
	v_mov_b32_e32 v3, v7
	v_mov_b32_e32 v4, v8
	v_mov_b32_e32 v5, v9
	v_mov_b32_e32 v88, v120
	v_mov_b32_e32 v89, v121
	v_mov_b32_e32 v90, v122
	v_mov_b32_e32 v91, v123
	v_mov_b32_e32 v92, v124
	v_mov_b32_e32 v93, v125
	v_mov_b32_e32 v94, v126
	v_mov_b32_e32 v95, v127
	v_mov_b32_e32 v96, v128
	v_mov_b32_e32 v97, v129
	v_mov_b32_e32 v98, v130
	v_mov_b32_e32 v99, v131
	v_mov_b32_e32 v100, v132
	v_mov_b32_e32 v101, v133
	v_mov_b32_e32 v102, v134
	v_mov_b32_e32 v103, v135
	v_mov_b32_e32 v104, v136
	v_mov_b32_e32 v105, v137
	v_mov_b32_e32 v106, v138
	v_mov_b32_e32 v107, v139
	v_mov_b32_e32 v108, v140
	v_mov_b32_e32 v109, v141
	v_mov_b32_e32 v110, v142
	v_mov_b32_e32 v111, v143
	v_mov_b32_e32 v112, v144
	v_mov_b32_e32 v113, v145
	v_mov_b32_e32 v114, v146
	v_mov_b32_e32 v115, v147
	v_mov_b32_e32 v116, v148
	v_mov_b32_e32 v117, v149
	v_mov_b32_e32 v118, v150
	v_mov_b32_e32 v119, v151
	s_and_saveexec_b64 s[16:17], s[0:1]
	s_cbranch_execz .Lnrm2_nopf
	v_add_u32_e32 v156, 0xfffff000, v47
	v_lshrrev_b32_e32 v156, 12, v156
	v_add_u32_e32 v156, 1, v156
	s_movk_i32 s0, 0xfff
	v_cmp_lt_i32_e32 vcc, s0, v47
	v_mov_b64_e32 v[152:153], s[8:9]
	s_nop 1
	v_cndmask_b32_e32 v156, 0, v156, vcc
	s_nop 0
	v_mad_u64_u32 v[152:153], s[0:1], v156, s89, v[152:153]
	s_mov_b64 s[0:1], 0x1000
	s_nop 0
	v_lshl_add_u64 v[152:153], v[152:153], 0, v[0:1]
	v_lshl_add_u64 v[154:155], v[152:153], 0, s[0:1]
	global_load_dwordx4 v[120:123], v[152:153], off
	global_load_dwordx4 v[124:127], v[152:153], off offset:1024
	global_load_dwordx4 v[128:131], v[152:153], off offset:2048
	global_load_dwordx4 v[132:135], v[152:153], off offset:3072
	global_load_dwordx4 v[136:139], v[154:155], off
	global_load_dwordx4 v[140:143], v[154:155], off offset:1024
	global_load_dwordx4 v[144:147], v[154:155], off offset:2048
	global_load_dwordx4 v[148:151], v[154:155], off offset:3072
	global_load_dwordx4 v[14:17], v[38:39], off
	global_load_dwordx4 v[18:21], v[38:39], off offset:1024
	global_load_dwordx4 v[22:25], v[38:39], off offset:2048
	global_load_dwordx4 v[6:9], v[38:39], off offset:3072
.Lnrm2_nopf:
	s_or_b64 exec, exec, s[16:17]
	v_pk_mul_f32 v[66:67], v[30:31], v[30:31]
	v_pk_mul_f32 v[68:69], v[26:27], v[26:27]
	v_pk_mul_f32 v[62:63], v[32:33], v[32:33]
	v_pk_mul_f32 v[64:65], v[28:29], v[28:29]
	v_mov_b32_e32 v70, v66
	v_mov_b32_e32 v71, v68
	v_mov_b32_e32 v68, v67
	v_pk_add_f32 v[66:67], v[70:71], v[68:69]
	v_mov_b32_e32 v68, v62
	v_mov_b32_e32 v69, v64
	v_pk_mul_f32 v[58:59], v[2:3], v[2:3]
	v_pk_mul_f32 v[60:61], v[10:11], v[10:11]
	v_pk_add_f32 v[66:67], v[68:69], v[66:67]
	v_mov_b32_e32 v64, v63
	v_pk_mul_f32 v[48:49], v[4:5], v[4:5]
	v_pk_mul_f32 v[50:51], v[12:13], v[12:13]
	v_pk_add_f32 v[62:63], v[64:65], v[66:67]
	v_mov_b32_e32 v64, v58
	v_mov_b32_e32 v65, v60
	v_mov_b32_e32 v60, v59
	v_pk_add_f32 v[58:59], v[64:65], v[60:61]
	v_mov_b32_e32 v60, v48
	v_mov_b32_e32 v61, v50
	v_pk_add_f32 v[58:59], v[60:61], v[58:59]
	v_mov_b32_e32 v50, v49
	v_pk_add_f32 v[48:49], v[50:51], v[58:59]
	v_add_f32_e32 v43, v62, v63
	v_lshl_add_u64 v[38:39], v[38:39], 0, s[12:13]
	v_add_f32_e32 v43, v49, v43
	v_add_f32_e32 v43, v48, v43
	s_nop 0
	ds_bpermute_b32 v41, v52, v43
	s_waitcnt lgkmcnt(0)
	v_add_f32_e32 v41, v43, v41
	ds_bpermute_b32 v43, v53, v41
	s_waitcnt lgkmcnt(0)
	v_add_f32_e32 v41, v41, v43
	ds_bpermute_b32 v43, v54, v41
	s_waitcnt lgkmcnt(0)
	v_add_f32_e32 v41, v41, v43
	ds_bpermute_b32 v43, v55, v41
	s_waitcnt lgkmcnt(0)
	v_add_f32_e32 v41, v41, v43
	ds_bpermute_b32 v43, v56, v41
	s_waitcnt lgkmcnt(0)
	v_add_f32_e32 v41, v41, v43
	ds_bpermute_b32 v43, v57, v41
	s_waitcnt lgkmcnt(0)
	v_add_f32_e32 v41, v41, v43
	v_fmamk_f32 v41, v41, 0x3a800000, v230
	v_cmp_gt_f32_e32 vcc, s95, v41
	v_mul_f32_e32 v43, 0x4b800000, v41
	s_nop 0
	v_cndmask_b32_e32 v41, v41, v43, vcc
	v_rsq_f32_e32 v41, v41
	s_nop 0
	v_mul_f32_e32 v43, 0x45800000, v41
	v_cndmask_b32_e32 v158, v41, v43, vcc
	s_nop 0
	v_pk_mul_f32 v[30:31], v[30:31], v[158:159] op_sel_hi:[1,0]
	v_pk_mul_f32 v[32:33], v[32:33], v[158:159] op_sel_hi:[1,0]
	v_pk_mul_f32 v[26:27], v[26:27], v[158:159] op_sel_hi:[1,0]
	v_pk_mul_f32 v[28:29], v[28:29], v[158:159] op_sel_hi:[1,0]
	v_pk_mul_f32 v[10:11], v[10:11], v[158:159] op_sel_hi:[1,0]
	v_pk_mul_f32 v[12:13], v[12:13], v[158:159] op_sel_hi:[1,0]
	v_pk_mul_f32 v[2:3], v[2:3], v[158:159] op_sel_hi:[1,0]
	v_pk_mul_f32 v[4:5], v[4:5], v[158:159] op_sel_hi:[1,0]
	v_pk_mul_f32 v[30:31], v[72:73], v[30:31]
	v_pk_mul_f32 v[32:33], v[74:75], v[32:33]
	v_pk_add_f32 v[58:59], v[104:105], 1.0 op_sel_hi:[1,0]
	v_pk_add_f32 v[60:61], v[106:107], 1.0 op_sel_hi:[1,0]
	s_nop 0
	v_pk_fma_f32 v[30:31], v[58:59], v[30:31], v[88:89]
	v_pk_fma_f32 v[32:33], v[32:33], v[60:61], v[90:91]
	v_cvt_pk_bf16_f32 v30, v30, v31
	v_cvt_pk_bf16_f32 v31, v32, v33
	global_store_dwordx2 v[36:37], v[30:31], off
	v_pk_mul_f32 v[26:27], v[76:77], v[26:27]
	v_pk_mul_f32 v[28:29], v[78:79], v[28:29]
	v_pk_add_f32 v[58:59], v[108:109], 1.0 op_sel_hi:[1,0]
	v_pk_add_f32 v[60:61], v[110:111], 1.0 op_sel_hi:[1,0]
	s_nop 0
	v_pk_fma_f32 v[26:27], v[58:59], v[26:27], v[92:93]
	v_pk_fma_f32 v[28:29], v[28:29], v[60:61], v[94:95]
	v_cvt_pk_bf16_f32 v26, v26, v27
	v_cvt_pk_bf16_f32 v27, v28, v29
	global_store_dwordx2 v[36:37], v[26:27], off offset:512
	v_pk_mul_f32 v[10:11], v[80:81], v[10:11]
	v_pk_mul_f32 v[12:13], v[82:83], v[12:13]
	v_pk_add_f32 v[58:59], v[112:113], 1.0 op_sel_hi:[1,0]
	v_pk_add_f32 v[60:61], v[114:115], 1.0 op_sel_hi:[1,0]
	s_nop 0
	v_pk_fma_f32 v[10:11], v[58:59], v[10:11], v[96:97]
	v_pk_fma_f32 v[12:13], v[12:13], v[60:61], v[98:99]
	v_cvt_pk_bf16_f32 v10, v10, v11
	v_cvt_pk_bf16_f32 v11, v12, v13
	global_store_dwordx2 v[36:37], v[10:11], off offset:1024
	v_pk_mul_f32 v[2:3], v[84:85], v[2:3]
	v_pk_mul_f32 v[4:5], v[86:87], v[4:5]
	v_pk_add_f32 v[58:59], v[116:117], 1.0 op_sel_hi:[1,0]
	v_pk_add_f32 v[60:61], v[118:119], 1.0 op_sel_hi:[1,0]
	s_nop 0
	v_pk_fma_f32 v[2:3], v[58:59], v[2:3], v[100:101]
	v_pk_fma_f32 v[4:5], v[4:5], v[60:61], v[102:103]
	v_cvt_pk_bf16_f32 v2, v2, v3
	v_cvt_pk_bf16_f32 v3, v4, v5
	global_store_dwordx2 v[36:37], v[2:3], off offset:1536
	v_lshl_add_u64 v[36:37], v[36:37], 0, s[10:11]
	v_mov_b32_e32 v46, v47
	s_andn2_b64 exec, exec, s[14:15]
	s_cbranch_execz .LBB0_100
	s_branch .LBB0_98

.LBB0_181:
	s_or_b64 exec, exec, s[0:1]
	v_mov_b32_e32 v0, s33
	s_waitcnt lgkmcnt(0)
	s_barrier
	ds_read_b32 v0, v0
	s_movk_i32 s0, 0xcf
	s_waitcnt lgkmcnt(0)
	v_cmp_lt_i32_e32 vcc, s0, v0
	v_readfirstlane_b32 s3, v0
	s_mov_b64 s[0:1], -1
	s_cbranch_vccnz .LBB0_178
	s_add_i32 s98, s3, 48
	s_sub_i32 s99, s3, 8
	s_cmp_lt_u32 s99, 128
	s_cselect_b32 s98, s98, s3
	s_sub_i32 s99, s3, 136
	s_sub_i32 vcc_lo, s3, 128
	s_cmp_lt_u32 s99, 48
	s_cselect_b32 s3, vcc_lo, s98
	s_cmp_gt_i32 s3, 7
	s_cbranch_scc0 .LBB0_307
	s_cmp_gt_u32 s3, 39
	s_cbranch_scc0 .LBB0_261
	s_cmp_gt_u32 s3, 55
	s_cbranch_scc0 .LBB0_230
	s_cmpk_gt_u32 s3, 0xb7
	s_cbranch_scc0 .LBB0_214
	s_cmpk_gt_u32 s3, 0xc7
	s_cbranch_scc0 .LBB0_198
	v_readlane_b32 s0, v254, 52
	s_add_i32 s0, s0, s3
	s_lshr_b32 s4, s0, 2
	s_and_b32 s2, s3, 3
	v_mov_b32_e32 v102, v228
	s_lshl_b32 s0, s4, 19
	v_readlane_b32 s1, v254, 46
	v_mov_b32_e32 v10, v228
	s_add_u32 s0, s1, s0
	v_readlane_b32 s1, v254, 49
	s_addc_u32 s1, s1, 0
	v_ashrrev_i32_e32 v12, 3, v10
	s_lshl_b32 s5, s2, 17
	v_lshlrev_b32_e32 v0, 3, v10
	v_ashrrev_i32_e32 v13, 31, v12
	v_readlane_b32 s8, v254, 60
	s_add_u32 s0, s0, s5
	v_and_b32_e32 v11, 56, v0
	v_lshlrev_b64 v[90:91], 10, v[12:13]
	v_readlane_b32 s9, v254, 61
	s_addc_u32 s1, s1, 0
	v_lshlrev_b32_e32 v0, 1, v11
	v_lshl_add_u64 v[92:93], s[8:9], 0, v[90:91]
	s_mov_b64 s[6:7], 0x10000
	v_lshl_add_u64 v[94:95], v[90:91], 0, s[6:7]
	v_lshl_add_u64 v[98:99], v[92:93], 0, s[42:43]
	v_lshl_add_u64 v[14:15], s[0:1], 0, v[0:1]
	s_mov_b32 s5, 8
	v_lshl_add_u64 v[2:3], v[92:93], 0, v[0:1]
	v_lshl_add_u64 v[96:97], s[8:9], 0, v[94:95]
	v_lshl_add_u64 v[6:7], v[98:99], 0, v[0:1]
	v_lshl_add_u64 v[100:101], v[92:93], 0, s[84:85]
	v_lshl_add_u64 v[16:17], v[14:15], 0, v[90:91]
	s_barrier
	v_lshl_add_u64 v[4:5], v[96:97], 0, v[0:1]
	global_load_dwordx4 v[66:69], v[2:3], off
	global_load_dwordx4 v[70:73], v[4:5], off
	v_lshl_add_u64 v[8:9], v[100:101], 0, v[0:1]
	global_load_dwordx4 v[74:77], v[6:7], off
	global_load_dwordx4 v[78:81], v[8:9], off
	v_lshl_add_u64 v[14:15], v[14:15], 0, v[94:95]
	global_load_dwordx4 v[82:85], v[16:17], off
	global_load_dwordx4 v[86:89], v[14:15], off
	v_mul_lo_u32 v103, v12, s87
	v_add_u32_e32 v104, 0, v0
	v_add_u32_e32 v12, v104, v103
	s_cmp_lt_i32 s5, 2
	s_waitcnt vmcnt(0)
	ds_write_b128 v12, v[66:69]
	ds_write_b128 v12, v[70:73] offset:9216
	ds_write_b128 v12, v[74:77] offset:18432
	ds_write_b128 v12, v[78:81] offset:27648
	ds_write_b128 v12, v[82:85] offset:36864
	ds_write_b128 v12, v[86:89] offset:46080
	s_cbranch_scc1 .LBB0_189
	global_load_dwordx4 v[66:69], v[2:3], off offset:128
	global_load_dwordx4 v[70:73], v[4:5], off offset:128
	global_load_dwordx4 v[74:77], v[6:7], off offset:128
	global_load_dwordx4 v[78:81], v[8:9], off offset:128
	v_lshl_add_u64 v[2:3], s[0:1], 0, v[90:91]
	v_lshl_add_u64 v[2:3], v[2:3], 0, v[0:1]
	v_lshl_add_u64 v[4:5], s[0:1], 0, v[94:95]
	v_lshl_add_u64 v[4:5], v[4:5], 0, v[0:1]
	global_load_dwordx4 v[82:85], v[2:3], off offset:128
	global_load_dwordx4 v[86:89], v[4:5], off offset:128

.LBB0_214:
	s_andn2_b64 vcc, exec, s[0:1]
	s_cbranch_vccnz .LBB0_229
	s_sub_i32 s2, s3, 56
	s_lshl_b32 s0, s2, 7
	s_and_b32 s0, s0, 0xf80
	s_or_b32 s6, s65, s0
	s_lshl_b32 s0, s2, 2
	s_and_b32 s4, s0, 0x7fffff80
	s_lshl_b32 s38, s4, 1
	v_readlane_b32 s0, v254, 41
	s_add_u32 s0, s0, s38
	v_readlane_b32 s1, v254, 45
	v_readlane_b32 s5, v254, 37
	v_mov_b32_e32 v30, v228
	s_addc_u32 s1, s1, 0
	s_add_i32 s4, s4, s5
	s_mulk_i32 s4, 0x1100
	v_and_b32_e32 v32, 31, v30
	s_mov_b32 s5, s39
	s_waitcnt vmcnt(0)
	v_ashrrev_i32_e32 v153, 7, v30
	s_lshl_b64 s[4:5], s[4:5], 1
	v_readlane_b32 s7, v254, 29
	v_or_b32_e32 v0, s6, v32
	s_add_u32 s4, s7, s4
	v_readlane_b32 s7, v254, 30
	v_lshl_add_u32 v2, v153, 5, v0
	s_addc_u32 s5, s7, s5
	v_ashrrev_i32_e32 v3, 31, v2
	v_readlane_b32 s6, v254, 50
	v_lshlrev_b64 v[2:3], 10, v[2:3]
	v_readlane_b32 s7, v254, 51
	v_bfe_u32 v162, v30, 6, 1
	v_bfe_u32 v31, v30, 5, 1
	v_lshl_add_u64 v[2:3], s[6:7], 0, v[2:3]
	v_lshl_add_u64 v[150:151], v[2:3], 0, s[38:39]
	v_lshlrev_b32_e32 v0, 7, v162
	v_lshlrev_b32_e32 v4, 4, v30
	v_lshl_add_u64 v[2:3], v[150:151], 0, v[0:1]
	v_lshlrev_b32_e32 v148, 4, v31
	v_mov_b32_e32 v149, v1
	v_ashrrev_i32_e32 v18, 4, v30
	v_and_b32_e32 v156, 0x70, v4
	v_mov_b32_e32 v157, v1
	v_lshl_add_u64 v[2:3], v[2:3], 0, v[148:149]
	v_ashrrev_i32_e32 v33, 3, v30
	v_and_b32_e32 v154, 0xf0, v4
	v_mov_b32_e32 v155, v1
	v_lshl_add_u64 v[14:15], s[4:5], 0, v[156:157]
	v_ashrrev_i32_e32 v19, 31, v18
	s_movk_i32 s6, 0x2200
	global_load_dwordx4 v[124:127], v[2:3], off
	global_load_dwordx4 v[120:123], v[2:3], off offset:32
	global_load_dwordx4 v[116:119], v[2:3], off offset:64
	global_load_dwordx4 v[112:115], v[2:3], off offset:96
	v_lshl_add_u64 v[2:3], s[0:1], 0, v[154:155]
	v_lshlrev_b64 v[20:21], 10, v[18:19]
	v_mad_i64_i32 v[6:7], s[0:1], v33, s6, v[14:15]
	v_lshl_add_u64 v[22:23], v[2:3], 0, v[20:21]
	s_mov_b32 s0, 0x8000
	v_add_co_u32_e32 v10, vcc, s0, v22
	v_add_u32_e32 v19, 64, v33
	s_waitcnt lgkmcnt(0)
	s_barrier
	global_load_dwordx4 v[2:5], v[22:23], off
	s_nop 0
	global_load_dwordx4 v[6:9], v[6:7], off
	v_addc_co_u32_e32 v11, vcc, 0, v23, vcc
	v_mad_i64_i32 v[14:15], s[0:1], v19, s6, v[14:15]
	global_load_dwordx4 v[10:13], v[10:11], off
	s_mov_b32 s0, 0x10000
	global_load_dwordx4 v[14:17], v[14:15], off
	v_mov_b64_e32 v[26:27], s[4:5]
	v_add_co_u32_e32 v24, vcc, s0, v22
	v_mad_i64_i32 v[28:29], s[0:1], v33, s6, v[26:27]
	s_nop 0
	v_addc_co_u32_e32 v25, vcc, 0, v23, vcc
	s_mov_b32 s0, 0x18000
	v_add_co_u32_e32 v22, vcc, s0, v22
	v_lshl_add_u64 v[28:29], v[28:29], 0, v[156:157]
	global_load_dwordx4 v[128:131], v[24:25], off
	global_load_dwordx4 v[132:135], v[28:29], off offset:128
	v_addc_co_u32_e32 v23, vcc, 0, v23, vcc
	v_mad_i64_i32 v[24:25], s[0:1], v19, s6, v[26:27]
	v_lshl_add_u64 v[24:25], v[24:25], 0, v[156:157]
	global_load_dwordx4 v[136:139], v[22:23], off
	global_load_dwordx4 v[140:143], v[24:25], off offset:128
	s_movk_i32 s1, 0x110
	v_mul_lo_u32 v164, v18, s1
	s_movk_i32 s1, 0x88
	v_mul_lo_u32 v165, v33, s1
	s_movk_i32 s1, 0x90
	v_mul_lo_u32 v193, v33, s1
	v_and_b32_e32 v192, 1, v228
	v_lshlrev_b32_e32 v192, 3, v192
	v_sub_u32_e32 v192, v156, v192
	v_add3_u32 v18, 0, v154, v164
	v_add3_u32 v19, 0, v192, v193
	v_add_u32_e32 v22, 0x4400, v19
	s_bfe_u32 s1, s2, 0x190005
	s_lshl_b32 s2, s1, 8
	v_readlane_b32 s4, v254, 35
	s_add_u32 s4, s2, s4
	s_waitcnt vmcnt(0)
	ds_write_b128 v18, v[2:5]
	ds_write2_b64 v22, v[6:7], v[8:9] offset1:2
	ds_write_b128 v18, v[10:13] offset:8704
	v_add_u32_e32 v2, 0x6800, v19
	v_and_b32_e32 v3, 64, v231
	v_add_u32_e32 v3, 64, v3
	ds_write2_b64 v2, v[14:15], v[16:17] offset1:2
	v_xor_b32_e32 v2, 32, v231
	v_cmp_lt_i32_e32 vcc, v2, v3
	v_or_b32_e32 v167, v0, v148
	s_addc_u32 s5, 0, 0
	v_cndmask_b32_e32 v2, v231, v2, vcc
	v_and_b32_e32 v0, 15, v30
	v_lshlrev_b32_e32 v149, 2, v2
	v_lshl_add_u64 v[2:3], s[4:5], 0, v[20:21]
	v_lshlrev_b32_e32 v0, 4, v0
	v_lshl_add_u64 v[158:159], v[2:3], 0, v[0:1]
	v_mad_i64_i32 v[2:3], s[4:5], v33, s6, 0
	v_and_b32_e32 v0, 7, v30
	s_mul_i32 s1, s1, 0x88000
	v_readlane_b32 s2, v254, 36
	s_waitcnt lgkmcnt(0)
	s_barrier
	v_lshl_or_b32 v2, v0, 4, v2
	s_add_i32 s38, s2, s1
	v_mov_b32_e32 v14, v1
	v_mov_b32_e32 v15, v1
	v_and_b32_e32 v155, 63, v30
	v_lshlrev_b32_e32 v152, 3, v31
	v_mul_u32_u24_e32 v163, 0x88, v32
	v_mul_u32_u24_e32 v194, 0x90, v32
	v_lshl_add_u32 v194, v31, 4, v194
	v_mul_u32_u24_e32 v166, 0x110, v32
	v_lshl_add_u64 v[160:161], s[38:39], 1, v[2:3]
	v_mov_b32_e32 v0, v1
	v_mov_b32_e32 v2, v1
	v_mov_b32_e32 v3, v1
	v_mov_b32_e32 v4, v1
	v_mov_b32_e32 v5, v1
	v_mov_b32_e32 v6, v1
	v_mov_b32_e32 v7, v1
	v_mov_b32_e32 v8, v1
	v_mov_b32_e32 v9, v1
	v_mov_b32_e32 v10, v1
	v_mov_b32_e32 v11, v1
	v_mov_b32_e32 v12, v1
	v_mov_b32_e32 v13, v1
	v_mov_b64_e32 v[30:31], v[14:15]
	v_mov_b64_e32 v[46:47], v[14:15]
	v_mov_b64_e32 v[62:63], v[14:15]
	v_mov_b64_e32 v[78:79], v[14:15]
	s_mov_b32 s0, 1
	v_mov_b32_e32 v157, 0xf149f2ca
	v_mov_b32_e32 v168, 0
	v_mov_b64_e32 v[28:29], v[12:13]
	v_mov_b64_e32 v[26:27], v[10:11]
	v_mov_b64_e32 v[24:25], v[8:9]
	v_mov_b64_e32 v[22:23], v[6:7]
	v_mov_b64_e32 v[20:21], v[4:5]
	v_mov_b64_e32 v[18:19], v[2:3]
	v_mov_b64_e32 v[16:17], v[0:1]
	v_mov_b64_e32 v[44:45], v[12:13]
	v_mov_b64_e32 v[42:43], v[10:11]
	v_mov_b64_e32 v[40:41], v[8:9]
	v_mov_b64_e32 v[38:39], v[6:7]
	v_mov_b64_e32 v[36:37], v[4:5]
	v_mov_b64_e32 v[34:35], v[2:3]
	v_mov_b64_e32 v[32:33], v[0:1]
	v_mov_b64_e32 v[60:61], v[12:13]
	v_mov_b64_e32 v[58:59], v[10:11]
	v_mov_b64_e32 v[56:57], v[8:9]
	v_mov_b64_e32 v[54:55], v[6:7]
	v_mov_b64_e32 v[52:53], v[4:5]
	v_mov_b64_e32 v[50:51], v[2:3]
	v_mov_b64_e32 v[48:49], v[0:1]
	v_mov_b64_e32 v[76:77], v[12:13]
	v_mov_b64_e32 v[74:75], v[10:11]
	v_mov_b64_e32 v[72:73], v[8:9]
	v_mov_b64_e32 v[70:71], v[6:7]
	v_mov_b64_e32 v[68:69], v[4:5]
	v_mov_b64_e32 v[66:67], v[2:3]
	v_mov_b64_e32 v[64:65], v[0:1]
	s_mov_b64 s[4:5], 0x10000
.LBB0_216:
	s_add_i32 s2, s0, -1
	s_bitcmp1_b32 s0, 0
	s_cselect_b32 s1, 0x8c00, 0
	s_add_i32 s1, s1, 0
	v_add3_u32 v2, s1, v192, v193
	v_add3_u32 v0, s1, v154, v164
	v_add_u32_e32 v3, 0x4400, v2
	s_waitcnt vmcnt(3)
	ds_write_b128 v0, v[128:131]
	s_waitcnt vmcnt(2)
	ds_write2_b64 v3, v[132:133], v[134:135] offset1:2
	s_waitcnt vmcnt(1)
	ds_write_b128 v0, v[136:139] offset:8704
	v_add_u32_e32 v0, 0x6800, v2
	s_cmpk_gt_u32 s2, 0x41
	s_waitcnt vmcnt(0)
	ds_write2_b64 v0, v[140:141], v[142:143] offset1:2
	s_cbranch_scc1 .LBB0_218
	v_lshl_add_u64 v[2:3], s[78:79], 0, v[158:159]
	v_add_co_u32_e32 v4, vcc, 0x188a0000, v2
	v_lshl_add_u64 v[6:7], s[78:79], 0, v[160:161]
	s_nop 0
	v_addc_co_u32_e32 v5, vcc, 0, v3, vcc
	v_add_co_u32_e32 v8, vcc, 0x1ae80000, v6
	s_nop 1
	v_addc_co_u32_e32 v9, vcc, 0, v7, vcc
	v_add_co_u32_e32 v2, vcc, 0x188a8000, v2
	global_load_dwordx4 v[128:131], v[4:5], off
	global_load_dwordx4 v[132:135], v[8:9], off offset:256
	v_addc_co_u32_e32 v3, vcc, 0, v3, vcc
	v_add_co_u32_e32 v4, vcc, 0x1af08000, v6
	s_nop 1
	v_addc_co_u32_e32 v5, vcc, 0, v7, vcc
	global_load_dwordx4 v[136:139], v[2:3], off
	global_load_dwordx4 v[140:143], v[4:5], off offset:256
.LBB0_218:
	s_bitcmp1_b32 s2, 0
	s_cselect_b32 s2, 0x8c00, 0
	s_add_i32 s2, s2, 0
	v_add3_u32 v0, s2, v167, v166
	v_add_u32_e32 v195, s2, v194
	ds_read_b128 v[2:5], v0
	ds_read_b128 v[10:13], v0 offset:8704
	ds_read_b128 v[6:9], v0 offset:32
	ds_read_b128 v[170:173], v0 offset:8736
	ds_read_b128 v[180:183], v0 offset:64
	ds_read_b128 v[188:191], v0 offset:8768
	ds_read_b128 v[184:187], v0 offset:96
	ds_read_b128 v[176:179], v0 offset:8800
	ds_read_b128 v[144:147], v195 offset:17408
	s_mov_b32 s2, 0x41000000
	s_waitcnt lgkmcnt(8)
	v_mfma_f32_32x32x16_bf16 v[96:111], v[2:5], v[124:127], 0
	s_waitcnt lgkmcnt(7)
	v_mfma_f32_32x32x16_bf16 v[80:95], v[10:13], v[124:127], 0
	s_waitcnt lgkmcnt(6)
	v_mfma_f32_32x32x16_bf16 v[96:111], v[6:9], v[120:123], v[96:111]
	s_waitcnt lgkmcnt(5)
	v_mfma_f32_32x32x16_bf16 v[80:95], v[170:173], v[120:123], v[80:95]
	s_waitcnt lgkmcnt(4)
	v_mfma_f32_32x32x16_bf16 v[96:111], v[180:183], v[116:119], v[96:111]
	s_waitcnt lgkmcnt(3)
	v_mfma_f32_32x32x16_bf16 v[80:95], v[188:191], v[116:119], v[80:95]
	s_waitcnt lgkmcnt(2)
	v_mfma_f32_32x32x16_bf16 v[96:111], v[184:187], v[112:115], v[96:111]
	ds_read_b128 v[10:13], v195 offset:22016
	ds_read_b128 v[6:9], v195 offset:26624
	s_waitcnt lgkmcnt(3)
	v_mfma_f32_32x32x16_bf16 v[80:95], v[176:179], v[112:115], v[80:95]
	ds_read_b128 v[2:5], v195 offset:31232
	s_nop 6
	v_max_f32_e32 v209, v97, v97
	v_max_f32_e32 v211, v96, v96
	v_max_f32_e32 v209, v211, v209
	v_max3_f32 v211, v209, v98, v99
	v_max3_f32 v211, v211, v100, v101
	v_max3_f32 v211, v211, v102, v103
	v_max3_f32 v211, v211, v104, v105
	v_max3_f32 v211, v211, v106, v107
	v_max3_f32 v211, v211, v108, v109
	v_max3_f32 v211, v211, v110, v111
	v_max3_f32 v211, v211, v80, v81
	v_max3_f32 v211, v211, v82, v83
	v_max3_f32 v211, v211, v84, v85
	v_max3_f32 v211, v211, v86, v87
	v_max3_f32 v211, v211, v88, v89
	v_max3_f32 v211, v211, v90, v91
	v_max3_f32 v211, v211, v92, v93
	v_max3_f32 v171, v211, v94, v95
	ds_bpermute_b32 v172, v149, v171
	s_waitcnt lgkmcnt(0)
	v_max_f32_e32 v0, v172, v172
	v_max_f32_e32 v171, v171, v0
	v_sub_f32_e32 v0, v171, v157
	v_cmp_ge_f32_e32 vcc, s2, v0
	s_cmp_eq_u64 vcc, exec
	v_mov_b32_e32 v0, 1.0
	s_cbranch_scc1 .LBB0_220
	v_max_f32_e32 v0, v171, v171
	v_max_f32_e32 v171, v157, v157
	v_max_f32_e32 v171, v171, v0
	v_sub_f32_e32 v0, v157, v171
	v_exp_f32_e32 v0, v0
	v_mov_b32_e32 v157, v171
	v_pk_mul_f32 v[78:79], v[78:79], v[0:1] op_sel_hi:[1,0]
	v_pk_mul_f32 v[76:77], v[76:77], v[0:1] op_sel_hi:[1,0]
	v_pk_mul_f32 v[74:75], v[74:75], v[0:1] op_sel_hi:[1,0]
	v_pk_mul_f32 v[72:73], v[72:73], v[0:1] op_sel_hi:[1,0]
	v_pk_mul_f32 v[70:71], v[70:71], v[0:1] op_sel_hi:[1,0]
	v_pk_mul_f32 v[68:69], v[68:69], v[0:1] op_sel_hi:[1,0]
	v_pk_mul_f32 v[66:67], v[66:67], v[0:1] op_sel_hi:[1,0]
	v_pk_mul_f32 v[64:65], v[64:65], v[0:1] op_sel_hi:[1,0]
	v_pk_mul_f32 v[62:63], v[62:63], v[0:1] op_sel_hi:[1,0]
	v_pk_mul_f32 v[60:61], v[60:61], v[0:1] op_sel_hi:[1,0]
	v_pk_mul_f32 v[58:59], v[58:59], v[0:1] op_sel_hi:[1,0]
	v_pk_mul_f32 v[56:57], v[56:57], v[0:1] op_sel_hi:[1,0]
	v_pk_mul_f32 v[54:55], v[54:55], v[0:1] op_sel_hi:[1,0]
	v_pk_mul_f32 v[52:53], v[52:53], v[0:1] op_sel_hi:[1,0]
	v_pk_mul_f32 v[50:51], v[50:51], v[0:1] op_sel_hi:[1,0]
	v_pk_mul_f32 v[48:49], v[48:49], v[0:1] op_sel_hi:[1,0]
	v_pk_mul_f32 v[46:47], v[46:47], v[0:1] op_sel_hi:[1,0]
	v_pk_mul_f32 v[44:45], v[44:45], v[0:1] op_sel_hi:[1,0]
	v_pk_mul_f32 v[42:43], v[42:43], v[0:1] op_sel_hi:[1,0]
	v_pk_mul_f32 v[40:41], v[40:41], v[0:1] op_sel_hi:[1,0]
	v_pk_mul_f32 v[38:39], v[38:39], v[0:1] op_sel_hi:[1,0]
	v_pk_mul_f32 v[36:37], v[36:37], v[0:1] op_sel_hi:[1,0]
	v_pk_mul_f32 v[34:35], v[34:35], v[0:1] op_sel_hi:[1,0]
	v_pk_mul_f32 v[32:33], v[32:33], v[0:1] op_sel_hi:[1,0]
	v_pk_mul_f32 v[30:31], v[30:31], v[0:1] op_sel_hi:[1,0]
	v_pk_mul_f32 v[28:29], v[28:29], v[0:1] op_sel_hi:[1,0]
	v_pk_mul_f32 v[26:27], v[26:27], v[0:1] op_sel_hi:[1,0]
	v_pk_mul_f32 v[24:25], v[24:25], v[0:1] op_sel_hi:[1,0]
	v_pk_mul_f32 v[22:23], v[22:23], v[0:1] op_sel_hi:[1,0]
	v_pk_mul_f32 v[20:21], v[20:21], v[0:1] op_sel_hi:[1,0]
	v_pk_mul_f32 v[18:19], v[18:19], v[0:1] op_sel_hi:[1,0]
	v_pk_mul_f32 v[16:17], v[16:17], v[0:1] op_sel_hi:[1,0]
.LBB0_220:
	ds_read_b128 v[212:215], v195 offset:17440
	ds_read_b128 v[216:219], v195 offset:22048
	ds_read_b128 v[220:223], v195 offset:26656
	ds_read_b128 v[224:227], v195 offset:31264
	v_sub_f32_e32 v97, v97, v157
	v_sub_f32_e32 v96, v96, v157
	v_exp_f32_e32 v177, v97
	v_sub_f32_e32 v97, v98, v157
	v_exp_f32_e32 v176, v96
	v_exp_f32_e32 v178, v97
	v_sub_f32_e32 v97, v99, v157
	v_sub_f32_e32 v96, v100, v157
	v_exp_f32_e32 v179, v97
	v_exp_f32_e32 v180, v96
	v_sub_f32_e32 v97, v101, v157
	v_sub_f32_e32 v96, v102, v157
	v_exp_f32_e32 v181, v97
	v_exp_f32_e32 v182, v96
	v_sub_f32_e32 v97, v103, v157
	v_add_f32_e32 v208, v176, v177
	v_exp_f32_e32 v183, v97
	v_add_f32_e32 v208, v178, v208
	v_add_f32_e32 v208, v179, v208
	v_add_f32_e32 v208, v180, v208
	v_add_f32_e32 v208, v181, v208
	v_add_f32_e32 v208, v182, v208
	v_add_f32_e32 v208, v183, v208
	v_cvt_pk_bf16_f32 v176, v176, v177
	v_cvt_pk_bf16_f32 v177, v178, v179
	v_cvt_pk_bf16_f32 v178, v180, v181
	v_cvt_pk_bf16_f32 v179, v182, v183
	s_nop 0
	v_sub_f32_e32 v97, v104, v157
	v_sub_f32_e32 v96, v105, v157
	v_mfma_f32_32x32x16_bf16 v[64:79], v[144:147], v[176:179], v[64:79]
	v_exp_f32_e32 v184, v97
	v_exp_f32_e32 v185, v96
	v_sub_f32_e32 v97, v106, v157
	v_sub_f32_e32 v96, v107, v157
	v_mfma_f32_32x32x16_bf16 v[48:63], v[10:13], v[176:179], v[48:63]
	v_exp_f32_e32 v186, v97
	v_exp_f32_e32 v187, v96
	v_sub_f32_e32 v97, v108, v157
	v_sub_f32_e32 v96, v109, v157
	v_mfma_f32_32x32x16_bf16 v[32:47], v[6:9], v[176:179], v[32:47]
	v_exp_f32_e32 v188, v97
	v_exp_f32_e32 v189, v96
	v_sub_f32_e32 v97, v110, v157
	v_sub_f32_e32 v96, v111, v157
	s_waitcnt lgkmcnt(4)
	v_mfma_f32_32x32x16_bf16 v[16:31], v[2:5], v[176:179], v[16:31]
	v_exp_f32_e32 v190, v97
	v_exp_f32_e32 v191, v96
	ds_read_b128 v[6:9], v195 offset:22080
	ds_read_b128 v[10:13], v195 offset:26688
	ds_read_b128 v[2:5], v195 offset:31296
	v_add_f32_e32 v208, v184, v208
	v_add_f32_e32 v208, v185, v208
	v_add_f32_e32 v208, v186, v208
	v_add_f32_e32 v208, v187, v208
	v_add_f32_e32 v208, v188, v208
	v_add_f32_e32 v208, v189, v208
	v_add_f32_e32 v208, v190, v208
	v_add_f32_e32 v208, v191, v208
	v_cvt_pk_bf16_f32 v144, v184, v185
	v_cvt_pk_bf16_f32 v145, v186, v187
	v_cvt_pk_bf16_f32 v146, v188, v189
	v_cvt_pk_bf16_f32 v147, v190, v191
	v_sub_f32_e32 v97, v80, v157
	v_sub_f32_e32 v96, v81, v157
	s_waitcnt lgkmcnt(3)
	v_mfma_f32_32x32x16_bf16 v[64:79], v[212:215], v[144:147], v[64:79]
	v_exp_f32_e32 v102, v97
	v_exp_f32_e32 v104, v96
	v_sub_f32_e32 v97, v82, v157
	v_sub_f32_e32 v96, v83, v157
	v_mfma_f32_32x32x16_bf16 v[48:63], v[216:219], v[144:147], v[48:63]
	v_exp_f32_e32 v106, v97
	v_exp_f32_e32 v101, v96
	ds_read_b128 v[80:83], v195 offset:17472
	v_sub_f32_e32 v97, v84, v157
	v_sub_f32_e32 v96, v85, v157
	v_mfma_f32_32x32x16_bf16 v[32:47], v[220:223], v[144:147], v[32:47]
	v_exp_f32_e32 v103, v97
	v_exp_f32_e32 v105, v96
	v_sub_f32_e32 v97, v86, v157
	v_sub_f32_e32 v96, v87, v157
	v_mfma_f32_32x32x16_bf16 v[16:31], v[224:227], v[144:147], v[16:31]
	v_exp_f32_e32 v107, v97
	v_exp_f32_e32 v108, v96
	v_add_f32_e32 v208, v102, v208
	v_add_f32_e32 v208, v104, v208
	v_add_f32_e32 v208, v106, v208
	v_add_f32_e32 v208, v101, v208
	v_add_f32_e32 v208, v103, v208
	v_add_f32_e32 v208, v105, v208
	v_add_f32_e32 v208, v107, v208
	v_add_f32_e32 v208, v108, v208
	v_cvt_pk_bf16_f32 v144, v102, v104
	v_cvt_pk_bf16_f32 v145, v106, v101
	v_cvt_pk_bf16_f32 v146, v103, v105
	v_cvt_pk_bf16_f32 v147, v107, v108
	v_sub_f32_e32 v97, v88, v157
	v_sub_f32_e32 v96, v89, v157
	s_waitcnt lgkmcnt(0)
	v_mfma_f32_32x32x16_bf16 v[64:79], v[80:83], v[144:147], v[64:79]
	v_exp_f32_e32 v109, v97
	v_exp_f32_e32 v110, v96
	v_sub_f32_e32 v97, v90, v157
	v_sub_f32_e32 v96, v91, v157
	v_mfma_f32_32x32x16_bf16 v[48:63], v[6:9], v[144:147], v[48:63]
	v_exp_f32_e32 v111, v97
	v_exp_f32_e32 v171, v96
	v_sub_f32_e32 v97, v92, v157
	v_sub_f32_e32 v96, v93, v157
	v_mfma_f32_32x32x16_bf16 v[32:47], v[10:13], v[144:147], v[32:47]
	v_exp_f32_e32 v172, v97
	v_exp_f32_e32 v173, v96
	v_sub_f32_e32 v97, v94, v157
	v_sub_f32_e32 v96, v95, v157
	v_mfma_f32_32x32x16_bf16 v[16:31], v[2:5], v[144:147], v[16:31]
	v_exp_f32_e32 v174, v97
	v_exp_f32_e32 v175, v96
	ds_read_b128 v[84:87], v195 offset:17504
	ds_read_b128 v[88:91], v195 offset:22112
	ds_read_b128 v[92:95], v195 offset:26720
	ds_read_b128 v[96:99], v195 offset:31328
	v_add_f32_e32 v208, v109, v208
	v_add_f32_e32 v208, v110, v208
	v_add_f32_e32 v208, v111, v208
	v_add_f32_e32 v208, v171, v208
	v_add_f32_e32 v208, v172, v208
	v_add_f32_e32 v208, v173, v208
	v_add_f32_e32 v208, v174, v208
	v_add_f32_e32 v208, v175, v208
	v_cvt_pk_bf16_f32 v2, v109, v110
	v_cvt_pk_bf16_f32 v3, v111, v171
	v_cvt_pk_bf16_f32 v4, v172, v173
	v_cvt_pk_bf16_f32 v5, v174, v175
	s_mov_b64 s[6:7], 0x80
	v_lshl_add_u64 v[158:159], v[158:159], 0, s[4:5]
	v_lshl_add_u64 v[160:161], v[160:161], 0, s[6:7]
	s_waitcnt lgkmcnt(0)
	s_barrier
	v_mfma_f32_32x32x16_bf16 v[64:79], v[84:87], v[2:5], v[64:79]
	v_mfma_f32_32x32x16_bf16 v[48:63], v[88:91], v[2:5], v[48:63]
	v_mfma_f32_32x32x16_bf16 v[32:47], v[92:95], v[2:5], v[32:47]
	v_mfma_f32_32x32x16_bf16 v[16:31], v[96:99], v[2:5], v[16:31]
	v_mov_b32_e32 v14, v208
	s_add_i32 s0, s0, 1
	s_cmpk_eq_i32 s0, 0x44
	v_fmac_f32_e32 v14, v168, v0
	s_cbranch_scc1 .LBB0_222
	v_mov_b32_e32 v168, v14
	s_branch .LBB0_216
.LBB0_222:
	v_add3_u32 v0, s1, v167, v166
	ds_read_b128 v[2:5], v0
	s_mov_b32 s0, 0x41000000
	s_waitcnt lgkmcnt(0)
	v_mfma_f32_32x32x16_bf16 v[96:111], v[2:5], v[124:127], 0
	ds_read_b128 v[2:5], v0 offset:8704
	s_waitcnt lgkmcnt(0)
	v_mfma_f32_32x32x16_bf16 v[80:95], v[2:5], v[124:127], 0
	ds_read_b128 v[2:5], v0 offset:32
	s_waitcnt lgkmcnt(0)
	v_mfma_f32_32x32x16_bf16 v[96:111], v[2:5], v[120:123], v[96:111]
	ds_read_b128 v[2:5], v0 offset:8736
	s_waitcnt lgkmcnt(0)
	v_mfma_f32_32x32x16_bf16 v[80:95], v[2:5], v[120:123], v[80:95]
	ds_read_b128 v[2:5], v0 offset:64
	s_waitcnt lgkmcnt(0)
	v_mfma_f32_32x32x16_bf16 v[96:111], v[2:5], v[116:119], v[96:111]
	ds_read_b128 v[2:5], v0 offset:96
	ds_read_b128 v[10:13], v0 offset:8768
	ds_read_b128 v[122:125], v0 offset:8800
	v_add_u32_e32 v0, s1, v163
	v_add_u32_e32 v195, s1, v194
	v_add_u32_e32 v0, v0, v152
	v_add_u32_e32 v121, 0x4000, v0
	v_add_u32_e32 v120, 0x5000, v0
	ds_read_b128 v[6:9], v195 offset:17408
	s_waitcnt lgkmcnt(3)
	v_mfma_f32_32x32x16_bf16 v[96:111], v[2:5], v[112:115], v[96:111]
	ds_read_b128 v[2:5], v195 offset:22016
	s_waitcnt lgkmcnt(3)
	v_mfma_f32_32x32x16_bf16 v[80:95], v[10:13], v[116:119], v[80:95]
	s_nop 8
	v_max_f32_e32 v15, v97, v97
	v_max_f32_e32 v126, v96, v96
	v_max_f32_e32 v15, v126, v15
	v_max3_f32 v10, v15, v98, v99
	v_max3_f32 v10, v10, v100, v101
	v_max3_f32 v10, v10, v102, v103
	v_max3_f32 v10, v10, v104, v105
	s_waitcnt lgkmcnt(2)
	v_mfma_f32_32x32x16_bf16 v[80:95], v[122:125], v[112:115], v[80:95]
	v_max3_f32 v10, v10, v106, v107
	v_max3_f32 v10, v10, v108, v109
	v_max3_f32 v10, v10, v110, v111
	v_add_u32_e32 v116, 0x6000, v0
	v_add_u32_e32 v15, 0x7000, v0
	ds_read_b128 v[112:115], v195 offset:26624
	s_nop 5
	v_max3_f32 v10, v10, v80, v81
	v_max3_f32 v10, v10, v82, v83
	v_max3_f32 v10, v10, v84, v85
	v_max3_f32 v10, v10, v86, v87
	v_max3_f32 v10, v10, v88, v89
	v_max3_f32 v10, v10, v90, v91
	v_max3_f32 v10, v10, v92, v93
	v_max3_f32 v117, v10, v94, v95
	ds_bpermute_b32 v118, v149, v117
	ds_read_b128 v[10:13], v195 offset:31232
	s_waitcnt lgkmcnt(1)
	v_max_f32_e32 v0, v118, v118
	v_max_f32_e32 v117, v117, v0
	v_sub_f32_e32 v0, v117, v157
	v_cmp_ge_f32_e32 vcc, s0, v0
	s_cmp_eq_u64 vcc, exec
	v_mov_b32_e32 v0, 1.0
	s_cbranch_scc1 .LBB0_224
	v_max_f32_e32 v0, v117, v117
	v_max_f32_e32 v117, v157, v157
	v_max_f32_e32 v117, v117, v0
	v_sub_f32_e32 v0, v157, v117
	v_exp_f32_e32 v0, v0
	v_mov_b32_e32 v157, v117
	v_pk_mul_f32 v[78:79], v[78:79], v[0:1] op_sel_hi:[1,0]
	v_pk_mul_f32 v[76:77], v[76:77], v[0:1] op_sel_hi:[1,0]
	v_pk_mul_f32 v[74:75], v[74:75], v[0:1] op_sel_hi:[1,0]
	v_pk_mul_f32 v[72:73], v[72:73], v[0:1] op_sel_hi:[1,0]
	v_pk_mul_f32 v[70:71], v[70:71], v[0:1] op_sel_hi:[1,0]
	v_pk_mul_f32 v[68:69], v[68:69], v[0:1] op_sel_hi:[1,0]
	v_pk_mul_f32 v[66:67], v[66:67], v[0:1] op_sel_hi:[1,0]
	v_pk_mul_f32 v[64:65], v[64:65], v[0:1] op_sel_hi:[1,0]
	v_pk_mul_f32 v[62:63], v[62:63], v[0:1] op_sel_hi:[1,0]
	v_pk_mul_f32 v[60:61], v[60:61], v[0:1] op_sel_hi:[1,0]
	v_pk_mul_f32 v[58:59], v[58:59], v[0:1] op_sel_hi:[1,0]
	v_pk_mul_f32 v[56:57], v[56:57], v[0:1] op_sel_hi:[1,0]
	v_pk_mul_f32 v[54:55], v[54:55], v[0:1] op_sel_hi:[1,0]
	v_pk_mul_f32 v[52:53], v[52:53], v[0:1] op_sel_hi:[1,0]
	v_pk_mul_f32 v[50:51], v[50:51], v[0:1] op_sel_hi:[1,0]
	v_pk_mul_f32 v[48:49], v[48:49], v[0:1] op_sel_hi:[1,0]
	v_pk_mul_f32 v[46:47], v[46:47], v[0:1] op_sel_hi:[1,0]
	v_pk_mul_f32 v[44:45], v[44:45], v[0:1] op_sel_hi:[1,0]
	v_pk_mul_f32 v[42:43], v[42:43], v[0:1] op_sel_hi:[1,0]
	v_pk_mul_f32 v[40:41], v[40:41], v[0:1] op_sel_hi:[1,0]
	v_pk_mul_f32 v[38:39], v[38:39], v[0:1] op_sel_hi:[1,0]
	v_pk_mul_f32 v[36:37], v[36:37], v[0:1] op_sel_hi:[1,0]
	v_pk_mul_f32 v[34:35], v[34:35], v[0:1] op_sel_hi:[1,0]
	v_pk_mul_f32 v[32:33], v[32:33], v[0:1] op_sel_hi:[1,0]
	v_pk_mul_f32 v[30:31], v[30:31], v[0:1] op_sel_hi:[1,0]
	v_pk_mul_f32 v[28:29], v[28:29], v[0:1] op_sel_hi:[1,0]
	v_pk_mul_f32 v[26:27], v[26:27], v[0:1] op_sel_hi:[1,0]
	v_pk_mul_f32 v[24:25], v[24:25], v[0:1] op_sel_hi:[1,0]
	v_pk_mul_f32 v[22:23], v[22:23], v[0:1] op_sel_hi:[1,0]
	v_pk_mul_f32 v[20:21], v[20:21], v[0:1] op_sel_hi:[1,0]
	v_pk_mul_f32 v[18:19], v[18:19], v[0:1] op_sel_hi:[1,0]
	v_pk_mul_f32 v[16:17], v[16:17], v[0:1] op_sel_hi:[1,0]
.LBB0_224:
	v_sub_f32_e32 v96, v96, v157
	v_exp_f32_e32 v117, v96
	v_sub_f32_e32 v96, v97, v157
	v_exp_f32_e32 v118, v96
	v_sub_f32_e32 v96, v98, v157
	v_exp_f32_e32 v119, v96
	v_sub_f32_e32 v96, v99, v157
	v_exp_f32_e32 v122, v96
	v_sub_f32_e32 v96, v100, v157
	v_exp_f32_e32 v100, v96
	v_sub_f32_e32 v96, v101, v157
	v_exp_f32_e32 v101, v96
	v_sub_f32_e32 v96, v102, v157
	v_exp_f32_e32 v102, v96
	v_sub_f32_e32 v96, v103, v157
	v_exp_f32_e32 v103, v96
	v_cvt_pk_bf16_f32 v96, v117, v118
	v_cvt_pk_bf16_f32 v97, v119, v122
	v_cvt_pk_bf16_f32 v98, v100, v101
	v_cvt_pk_bf16_f32 v99, v102, v103
	v_sub_f32_e32 v80, v80, v157
	v_sub_f32_e32 v83, v83, v157
	v_mfma_f32_32x32x16_bf16 v[48:63], v[2:5], v[96:99], v[48:63]
	v_sub_f32_e32 v2, v104, v157
	v_exp_f32_e32 v104, v2
	v_sub_f32_e32 v2, v105, v157
	v_exp_f32_e32 v105, v2
	v_sub_f32_e32 v2, v106, v157
	v_exp_f32_e32 v106, v2
	v_sub_f32_e32 v2, v107, v157
	v_exp_f32_e32 v107, v2
	v_sub_f32_e32 v2, v108, v157
	v_exp_f32_e32 v108, v2
	v_sub_f32_e32 v2, v109, v157
	v_exp_f32_e32 v109, v2
	ds_read_b128 v[2:5], v195 offset:17440
	v_mfma_f32_32x32x16_bf16 v[64:79], v[6:9], v[96:99], v[64:79]
	v_sub_f32_e32 v6, v110, v157
	v_cvt_pk_bf16_f32 v7, v106, v107
	v_cvt_pk_bf16_f32 v8, v108, v109
	v_sub_f32_e32 v86, v86, v157
	v_exp_f32_e32 v80, v80
	v_exp_f32_e32 v83, v83
	v_exp_f32_e32 v86, v86
	v_mfma_f32_32x32x16_bf16 v[32:47], v[112:115], v[96:99], v[32:47]
	s_waitcnt lgkmcnt(1)
	v_mfma_f32_32x32x16_bf16 v[16:31], v[10:13], v[96:99], v[16:31]
	v_exp_f32_e32 v96, v6
	v_sub_f32_e32 v6, v111, v157
	v_exp_f32_e32 v97, v6
	v_cvt_pk_bf16_f32 v6, v104, v105
	ds_read_b128 v[10:13], v195 offset:26656
	v_cvt_pk_bf16_f32 v9, v96, v97
	s_waitcnt lgkmcnt(1)
	s_nop 0
	v_mfma_f32_32x32x16_bf16 v[64:79], v[2:5], v[6:9], v[64:79]
	ds_read_b128 v[2:5], v195 offset:22048
	s_waitcnt lgkmcnt(0)
	v_mfma_f32_32x32x16_bf16 v[48:63], v[2:5], v[6:9], v[48:63]
	v_sub_f32_e32 v2, v81, v157
	v_exp_f32_e32 v81, v2
	v_sub_f32_e32 v2, v82, v157
	v_exp_f32_e32 v82, v2
	ds_read_b128 v[2:5], v195 offset:31264
	v_mfma_f32_32x32x16_bf16 v[32:47], v[10:13], v[6:9], v[32:47]
	v_sub_f32_e32 v10, v84, v157
	v_exp_f32_e32 v84, v10
	v_sub_f32_e32 v10, v85, v157
	v_exp_f32_e32 v85, v10
	ds_read_b128 v[10:13], v195 offset:17472
	s_waitcnt lgkmcnt(1)
	v_mfma_f32_32x32x16_bf16 v[16:31], v[2:5], v[6:9], v[16:31]
	v_sub_f32_e32 v2, v87, v157
	v_exp_f32_e32 v87, v2
	ds_read_b128 v[6:9], v195 offset:22080
	v_cvt_pk_bf16_f32 v2, v80, v81
	v_cvt_pk_bf16_f32 v3, v82, v83
	v_cvt_pk_bf16_f32 v4, v84, v85
	v_cvt_pk_bf16_f32 v5, v86, v87
	s_waitcnt lgkmcnt(1)
	s_nop 0
	v_mfma_f32_32x32x16_bf16 v[64:79], v[10:13], v[2:5], v[64:79]
	v_add_f32_e32 v10, 0, v117
	v_add_f32_e32 v10, v118, v10
	v_add_f32_e32 v98, v119, v10
	v_sub_f32_e32 v10, v88, v157
	v_exp_f32_e32 v88, v10
	ds_read_b128 v[10:13], v195 offset:26688
	s_waitcnt lgkmcnt(1)
	v_mfma_f32_32x32x16_bf16 v[48:63], v[6:9], v[2:5], v[48:63]
	v_sub_f32_e32 v6, v89, v157
	v_exp_f32_e32 v89, v6
	v_sub_f32_e32 v6, v90, v157
	v_exp_f32_e32 v90, v6
	v_sub_f32_e32 v6, v91, v157
	v_exp_f32_e32 v91, v6
	ds_read_b128 v[6:9], v195 offset:31296
	s_waitcnt lgkmcnt(1)
	v_mfma_f32_32x32x16_bf16 v[32:47], v[10:13], v[2:5], v[32:47]
	v_sub_f32_e32 v10, v92, v157
	v_exp_f32_e32 v92, v10
	v_sub_f32_e32 v10, v93, v157
	v_exp_f32_e32 v93, v10
	v_sub_f32_e32 v10, v94, v157
	v_exp_f32_e32 v94, v10
	ds_read_b128 v[10:13], v195 offset:17504
	s_waitcnt lgkmcnt(1)
	v_mfma_f32_32x32x16_bf16 v[16:31], v[6:9], v[2:5], v[16:31]
	v_sub_f32_e32 v2, v95, v157
	v_exp_f32_e32 v95, v2
	ds_read_b128 v[2:5], v195 offset:22112
	v_cvt_pk_bf16_f32 v6, v88, v89
	v_cvt_pk_bf16_f32 v7, v90, v91
	v_cvt_pk_bf16_f32 v8, v92, v93
	v_cvt_pk_bf16_f32 v9, v94, v95
	s_waitcnt lgkmcnt(1)
	s_nop 0
	v_mfma_f32_32x32x16_bf16 v[64:79], v[10:13], v[6:9], v[64:79]
	v_add_f32_e32 v10, v122, v98
	v_add_f32_e32 v10, v100, v10
	v_add_f32_e32 v10, v101, v10
	v_add_f32_e32 v10, v102, v10
	v_add_f32_e32 v10, v103, v10
	v_add_f32_e32 v98, v104, v10
	ds_read_b128 v[10:13], v195 offset:26720
	s_waitcnt lgkmcnt(1)
	v_mfma_f32_32x32x16_bf16 v[48:63], v[2:5], v[6:9], v[48:63]
	v_add_f32_e32 v2, v105, v98
	v_add_f32_e32 v2, v106, v2
	v_add_f32_e32 v2, v107, v2
	v_add_f32_e32 v2, v108, v2
	v_add_f32_e32 v2, v109, v2
	v_add_f32_e32 v2, v96, v2
	v_add_f32_e32 v2, v97, v2
	v_add_f32_e32 v2, v80, v2
	v_add_f32_e32 v2, v81, v2
	v_add_f32_e32 v2, v82, v2
	v_add_f32_e32 v2, v83, v2
	v_add_f32_e32 v2, v84, v2
	v_add_f32_e32 v2, v85, v2
	v_add_f32_e32 v2, v86, v2
	v_add_f32_e32 v2, v87, v2
	v_add_f32_e32 v2, v88, v2
	v_add_f32_e32 v2, v89, v2
	v_add_f32_e32 v2, v90, v2
	v_add_f32_e32 v2, v91, v2
	v_add_f32_e32 v2, v92, v2
	v_add_f32_e32 v2, v93, v2
	v_add_f32_e32 v2, v94, v2
	s_waitcnt lgkmcnt(0)
	v_mfma_f32_32x32x16_bf16 v[32:47], v[10:13], v[6:9], v[32:47]
	v_add_f32_e32 v10, v95, v2
	v_fmac_f32_e32 v10, v14, v0
	ds_bpermute_b32 v0, v149, v10
	ds_read_b128 v[2:5], v195 offset:31328
	s_waitcnt lgkmcnt(0)
	s_barrier
	s_waitcnt lgkmcnt(1)
	v_add_f32_e32 v0, v10, v0
	v_div_scale_f32 v10, s[0:1], v0, v0, 1.0
	v_rcp_f32_e32 v11, v10
	s_waitcnt lgkmcnt(0)
	v_mfma_f32_32x32x16_bf16 v[16:31], v[2:5], v[6:9], v[16:31]
	v_cmp_ne_u32_e64 s[0:1], 0, v162
	v_fma_f32 v2, -v10, v11, 1.0
	v_fmac_f32_e32 v11, v2, v11
	v_div_scale_f32 v2, vcc, 1.0, v0, 1.0
	v_mul_f32_e32 v3, v2, v11
	v_fma_f32 v4, -v10, v3, v2
	v_fmac_f32_e32 v3, v4, v11
	v_fma_f32 v2, -v10, v3, v2
	v_div_fmas_f32 v2, v2, v11, v3
	v_div_fixup_f32 v80, v2, v0, 1.0
	v_cmp_eq_u32_e32 vcc, 0, v162
	s_and_saveexec_b64 s[4:5], s[0:1]
	s_cbranch_execz .LBB0_226
	v_lshlrev_b32_e32 v2, 14, v153
	v_lshlrev_b32_e32 v3, 2, v155
	v_mul_f32_e32 v0, v64, v80
	v_add3_u32 v2, 0, v2, v3
	v_mul_f32_e32 v3, v65, v80
	ds_write2st64_b32 v2, v0, v3 offset1:1
	v_mul_f32_e32 v0, v66, v80
	v_mul_f32_e32 v3, v67, v80
	ds_write2st64_b32 v2, v0, v3 offset0:2 offset1:3
	v_mul_f32_e32 v0, v68, v80
	v_mul_f32_e32 v3, v69, v80
	ds_write2st64_b32 v2, v0, v3 offset0:4 offset1:5
	v_mul_f32_e32 v0, v70, v80
	v_mul_f32_e32 v3, v71, v80
	ds_write2st64_b32 v2, v0, v3 offset0:6 offset1:7
	v_mul_f32_e32 v0, v72, v80
	v_mul_f32_e32 v3, v73, v80
	ds_write2st64_b32 v2, v0, v3 offset0:8 offset1:9
	v_mul_f32_e32 v0, v74, v80
	v_mul_f32_e32 v3, v75, v80
	ds_write2st64_b32 v2, v0, v3 offset0:10 offset1:11
	v_mul_f32_e32 v0, v76, v80
	v_mul_f32_e32 v3, v77, v80
	ds_write2st64_b32 v2, v0, v3 offset0:12 offset1:13
	v_mul_f32_e32 v0, v78, v80
	v_mul_f32_e32 v3, v79, v80
	ds_write2st64_b32 v2, v0, v3 offset0:14 offset1:15
	v_mul_f32_e32 v0, v48, v80
	v_mul_f32_e32 v3, v49, v80
	ds_write2st64_b32 v2, v0, v3 offset0:16 offset1:17
	v_mul_f32_e32 v0, v50, v80
	v_mul_f32_e32 v3, v51, v80
	ds_write2st64_b32 v2, v0, v3 offset0:18 offset1:19
	v_mul_f32_e32 v0, v52, v80
	v_mul_f32_e32 v3, v53, v80
	ds_write2st64_b32 v2, v0, v3 offset0:20 offset1:21
	v_mul_f32_e32 v0, v54, v80
	v_mul_f32_e32 v3, v55, v80
	ds_write2st64_b32 v2, v0, v3 offset0:22 offset1:23
	v_mul_f32_e32 v0, v56, v80
	v_mul_f32_e32 v3, v57, v80
	ds_write2st64_b32 v2, v0, v3 offset0:24 offset1:25
	v_mul_f32_e32 v0, v58, v80
	v_mul_f32_e32 v3, v59, v80
	ds_write2st64_b32 v2, v0, v3 offset0:26 offset1:27
	v_mul_f32_e32 v0, v60, v80
	v_mul_f32_e32 v3, v61, v80
	ds_write2st64_b32 v2, v0, v3 offset0:28 offset1:29
	v_mul_f32_e32 v0, v62, v80
	v_mul_f32_e32 v3, v63, v80
	ds_write2st64_b32 v2, v0, v3 offset0:30 offset1:31
	v_mul_f32_e32 v0, v32, v80
	v_mul_f32_e32 v3, v33, v80
	ds_write2st64_b32 v2, v0, v3 offset0:32 offset1:33
	v_mul_f32_e32 v0, v34, v80
	v_mul_f32_e32 v3, v35, v80
	ds_write2st64_b32 v2, v0, v3 offset0:34 offset1:35
	v_mul_f32_e32 v0, v36, v80
	v_mul_f32_e32 v3, v37, v80
	ds_write2st64_b32 v2, v0, v3 offset0:36 offset1:37
	v_mul_f32_e32 v0, v38, v80
	v_mul_f32_e32 v3, v39, v80
	ds_write2st64_b32 v2, v0, v3 offset0:38 offset1:39
	v_mul_f32_e32 v0, v40, v80
	v_mul_f32_e32 v3, v41, v80
	ds_write2st64_b32 v2, v0, v3 offset0:40 offset1:41
	v_mul_f32_e32 v0, v42, v80
	v_mul_f32_e32 v3, v43, v80
	ds_write2st64_b32 v2, v0, v3 offset0:42 offset1:43
	v_mul_f32_e32 v0, v44, v80
	v_mul_f32_e32 v3, v45, v80
	ds_write2st64_b32 v2, v0, v3 offset0:44 offset1:45
	v_mul_f32_e32 v0, v46, v80
	v_mul_f32_e32 v3, v47, v80
	ds_write2st64_b32 v2, v0, v3 offset0:46 offset1:47
	v_mul_f32_e32 v0, v16, v80
	v_mul_f32_e32 v3, v17, v80
	ds_write2st64_b32 v2, v0, v3 offset0:48 offset1:49
	v_mul_f32_e32 v0, v18, v80
	v_mul_f32_e32 v3, v19, v80
	ds_write2st64_b32 v2, v0, v3 offset0:50 offset1:51
	v_mul_f32_e32 v0, v20, v80
	v_mul_f32_e32 v3, v21, v80
	ds_write2st64_b32 v2, v0, v3 offset0:52 offset1:53
	v_mul_f32_e32 v0, v22, v80
	v_mul_f32_e32 v3, v23, v80
	ds_write2st64_b32 v2, v0, v3 offset0:54 offset1:55
	v_mul_f32_e32 v0, v24, v80
	v_mul_f32_e32 v3, v25, v80
	ds_write2st64_b32 v2, v0, v3 offset0:56 offset1:57
	v_mul_f32_e32 v0, v26, v80
	v_mul_f32_e32 v3, v27, v80
	ds_write2st64_b32 v2, v0, v3 offset0:58 offset1:59
	v_mul_f32_e32 v0, v28, v80
	v_mul_f32_e32 v3, v29, v80
	ds_write2st64_b32 v2, v0, v3 offset0:60 offset1:61
	v_mul_f32_e32 v0, v30, v80
	v_mul_f32_e32 v3, v31, v80
	ds_write2st64_b32 v2, v0, v3 offset0:62 offset1:63
